# hynorm: the group-norm gain load joins the batched tile loads (was issued after the barrier and waited for alone)
# baseline (speedup 1.0000x reference)
.LBB0_783:
	s_and_b32 s0, s3, 0x380
	s_and_b32 s6, s12, 0xffffffc0
	v_add_u32_e32 v42, s0, v8
	s_ashr_i32 s7, s6, 31
	v_ashrrev_i32_e32 v43, 31, v42
	v_lshl_add_u64 v[40:41], s[6:7], 1, v[2:3]
	v_lshlrev_b64 v[42:43], 14, v[42:43]
	v_lshl_add_u64 v[42:43], v[40:41], 0, v[42:43]
	global_load_ushort v200, v[42:43], off
	v_add_u32_e32 v42, s0, v9
	v_ashrrev_i32_e32 v43, 31, v42
	v_lshlrev_b64 v[42:43], 14, v[42:43]
	v_lshl_add_u64 v[42:43], v[40:41], 0, v[42:43]
	global_load_ushort v201, v[42:43], off
	s_add_i32 s13, s13, s80
	s_add_i32 s12, s12, s14
	v_add_u32_e32 v42, s0, v10
	v_ashrrev_i32_e32 v43, 31, v42
	v_lshlrev_b64 v[42:43], 14, v[42:43]
	v_lshl_add_u64 v[42:43], v[40:41], 0, v[42:43]
	global_load_ushort v202, v[42:43], off
	v_add_u32_e32 v42, s0, v11
	v_ashrrev_i32_e32 v43, 31, v42
	v_lshlrev_b64 v[42:43], 14, v[42:43]
	v_lshl_add_u64 v[42:43], v[40:41], 0, v[42:43]
	global_load_ushort v203, v[42:43], off
	v_add_u32_e32 v42, s0, v12
	v_ashrrev_i32_e32 v43, 31, v42
	v_lshlrev_b64 v[42:43], 14, v[42:43]
	v_lshl_add_u64 v[42:43], v[40:41], 0, v[42:43]
	global_load_ushort v204, v[42:43], off
	v_add_u32_e32 v44, s6, v25
	v_add_u32_e32 v42, s0, v13
	v_ashrrev_i32_e32 v43, 31, v42
	v_lshlrev_b64 v[42:43], 14, v[42:43]
	v_lshl_add_u64 v[42:43], v[40:41], 0, v[42:43]
	global_load_ushort v205, v[42:43], off
	v_add_u32_e32 v42, s0, v14
	v_ashrrev_i32_e32 v43, 31, v42
	v_lshlrev_b64 v[42:43], 14, v[42:43]
	v_lshl_add_u64 v[42:43], v[40:41], 0, v[42:43]
	global_load_ushort v206, v[42:43], off
	v_add_u32_e32 v42, s0, v15
	v_ashrrev_i32_e32 v43, 31, v42
	v_lshlrev_b64 v[42:43], 14, v[42:43]
	v_lshl_add_u64 v[42:43], v[40:41], 0, v[42:43]
	global_load_ushort v207, v[42:43], off
	v_add_u32_e32 v42, s0, v16
	v_ashrrev_i32_e32 v43, 31, v42
	v_lshlrev_b64 v[42:43], 14, v[42:43]
	v_lshl_add_u64 v[42:43], v[40:41], 0, v[42:43]
	global_load_ushort v208, v[42:43], off
	v_add_u32_e32 v42, s0, v17
	v_ashrrev_i32_e32 v43, 31, v42
	v_lshlrev_b64 v[42:43], 14, v[42:43]
	v_lshl_add_u64 v[42:43], v[40:41], 0, v[42:43]
	global_load_ushort v209, v[42:43], off
	v_add_u32_e32 v42, s0, v18
	v_ashrrev_i32_e32 v43, 31, v42
	v_lshlrev_b64 v[42:43], 14, v[42:43]
	v_lshl_add_u64 v[42:43], v[40:41], 0, v[42:43]
	global_load_ushort v210, v[42:43], off
	v_add_u32_e32 v42, s0, v19
	v_ashrrev_i32_e32 v43, 31, v42
	v_lshlrev_b64 v[42:43], 14, v[42:43]
	v_lshl_add_u64 v[42:43], v[40:41], 0, v[42:43]
	global_load_ushort v211, v[42:43], off
	v_add_u32_e32 v42, s0, v20
	v_ashrrev_i32_e32 v43, 31, v42
	v_lshlrev_b64 v[42:43], 14, v[42:43]
	v_lshl_add_u64 v[42:43], v[40:41], 0, v[42:43]
	global_load_ushort v212, v[42:43], off
	v_add_u32_e32 v42, s0, v21
	v_ashrrev_i32_e32 v43, 31, v42
	v_lshlrev_b64 v[42:43], 14, v[42:43]
	v_lshl_add_u64 v[42:43], v[40:41], 0, v[42:43]
	global_load_ushort v213, v[42:43], off
	v_add_u32_e32 v42, s0, v22
	v_ashrrev_i32_e32 v43, 31, v42
	v_lshlrev_b64 v[42:43], 14, v[42:43]
	v_lshl_add_u64 v[42:43], v[40:41], 0, v[42:43]
	global_load_ushort v214, v[42:43], off
	v_add_u32_e32 v42, s0, v23
	v_ashrrev_i32_e32 v43, 31, v42
	v_lshlrev_b64 v[42:43], 14, v[42:43]
	v_lshl_add_u64 v[40:41], v[40:41], 0, v[42:43]
	global_load_ushort v215, v[40:41], off
	v_or_b32_e32 v39, s0, v0
	v_lshlrev_b32_e32 v39, 2, v39
	global_load_dwordx2 v[80:81], v39, s[20:21]
	s_waitcnt vmcnt(0)
	v_lshlrev_b32_e32 v200, 16, v200
	ds_write_b32 v34, v200
	v_lshlrev_b32_e32 v201, 16, v201
	v_mul_f32_e32 v45, v201, v201
	v_fmac_f32_e32 v45, v200, v200
	v_lshlrev_b32_e32 v202, 16, v202
	ds_write2_b32 v35, v201, v202 offset1:65
	v_fmac_f32_e32 v45, v202, v202
	v_lshlrev_b32_e32 v203, 16, v203
	v_fmac_f32_e32 v45, v203, v203
	v_lshlrev_b32_e32 v204, 16, v204
	ds_write2_b32 v35, v203, v204 offset0:130 offset1:195
	v_fmac_f32_e32 v45, v204, v204
	v_lshlrev_b32_e32 v205, 16, v205
	v_fmac_f32_e32 v45, v205, v205
	v_lshlrev_b32_e32 v206, 16, v206
	ds_write2_b32 v36, v205, v206 offset0:4 offset1:69
	v_fmac_f32_e32 v45, v206, v206
	v_lshlrev_b32_e32 v207, 16, v207
	v_fmac_f32_e32 v45, v207, v207
	v_lshlrev_b32_e32 v208, 16, v208
	ds_write2_b32 v36, v207, v208 offset0:134 offset1:199
	v_fmac_f32_e32 v45, v208, v208
	v_lshlrev_b32_e32 v209, 16, v209
	v_fmac_f32_e32 v45, v209, v209
	v_lshlrev_b32_e32 v210, 16, v210
	ds_write2_b32 v37, v209, v210 offset0:8 offset1:73
	v_fmac_f32_e32 v45, v210, v210
	v_lshlrev_b32_e32 v211, 16, v211
	v_fmac_f32_e32 v45, v211, v211
	v_lshlrev_b32_e32 v212, 16, v212
	ds_write2_b32 v37, v211, v212 offset0:138 offset1:203
	v_fmac_f32_e32 v45, v212, v212
	v_lshlrev_b32_e32 v213, 16, v213
	v_fmac_f32_e32 v45, v213, v213
	v_lshlrev_b32_e32 v214, 16, v214
	ds_write2_b32 v38, v213, v214 offset0:12 offset1:77
	v_fmac_f32_e32 v45, v214, v214
	v_lshlrev_b32_e32 v215, 16, v215
	ds_write_b32 v35, v215 offset:3640
	v_fmac_f32_e32 v45, v215, v215
	ds_write_b32 v24, v45 offset:33280
	s_waitcnt lgkmcnt(0)
	s_barrier
	s_lshl_b32 s0, s0, 1
	v_ashrrev_i32_e32 v45, 31, v44
	v_lshl_add_u64 v[82:83], v[4:5], 0, s[0:1]
	v_lshlrev_b64 v[44:45], 12, v[44:45]
	ds_read2_b64 v[40:43], v26 offset1:1
	ds_read2_b32 v[84:85], v26 offset0:65 offset1:66
	v_lshl_add_u64 v[86:87], v[82:83], 0, v[44:45]
	ds_read_b128 v[44:47], v1 offset:33280
	ds_read_b128 v[48:51], v1 offset:33296
	ds_read_b128 v[52:55], v1 offset:33536
	ds_read_b128 v[56:59], v1 offset:33792
	ds_read_b128 v[60:63], v1 offset:34048
	ds_read_b128 v[64:67], v1 offset:34304
	s_waitcnt lgkmcnt(5)
	v_pk_add_f32 v[44:45], v[44:45], 0 op_sel_hi:[1,0]
	ds_read_b128 v[68:71], v1 offset:34560
	ds_read_b128 v[72:75], v1 offset:34816
	s_waitcnt lgkmcnt(5)
	v_pk_add_f32 v[44:45], v[44:45], v[52:53]
	ds_read_b128 v[76:79], v1 offset:35072
	s_waitcnt lgkmcnt(5)
	v_pk_add_f32 v[44:45], v[44:45], v[56:57]
	v_pk_add_f32 v[46:47], v[46:47], 0 op_sel_hi:[1,0]
	s_waitcnt lgkmcnt(4)
	v_pk_add_f32 v[44:45], v[44:45], v[60:61]
	v_pk_add_f32 v[46:47], v[46:47], v[54:55]
	s_waitcnt lgkmcnt(3)
	v_pk_add_f32 v[44:45], v[44:45], v[64:65]
	v_pk_add_f32 v[46:47], v[46:47], v[58:59]
	s_waitcnt lgkmcnt(2)
	v_pk_add_f32 v[44:45], v[44:45], v[68:69]
	v_pk_add_f32 v[46:47], v[46:47], v[62:63]
	s_waitcnt lgkmcnt(1)
	v_pk_add_f32 v[44:45], v[44:45], v[72:73]
	v_pk_add_f32 v[46:47], v[46:47], v[66:67]
	s_waitcnt lgkmcnt(0)
	v_pk_add_f32 v[44:45], v[44:45], v[76:77]
	v_pk_add_f32 v[46:47], v[46:47], v[70:71]
	v_pk_fma_f32 v[44:45], v[44:45], s[2:3], v[6:7] op_sel_hi:[1,0,0]
	v_pk_add_f32 v[46:47], v[46:47], v[74:75]
	v_mul_f32_e32 v39, 0x4b800000, v44
	v_cmp_gt_f32_e64 s[4:5], s9, v44
	v_cmp_gt_f32_e32 vcc, s9, v45
	v_pk_add_f32 v[46:47], v[46:47], v[78:79]
	v_cndmask_b32_e64 v39, v44, v39, s[4:5]
	v_rsq_f32_e32 v39, v39
	v_pk_fma_f32 v[46:47], v[46:47], s[2:3], v[6:7] op_sel_hi:[1,0,0]
	v_pk_add_f32 v[48:49], v[48:49], 0 op_sel_hi:[1,0]
	v_mul_f32_e32 v44, 0x45800000, v39
	v_cndmask_b32_e64 v39, v39, v44, s[4:5]
	v_mul_f32_e32 v40, v40, v39
	v_mul_f32_e32 v39, v84, v39
	v_cmp_gt_f32_e64 s[4:5], s9, v46
	s_waitcnt vmcnt(0)
	v_mul_f32_e32 v40, v80, v40
	v_mul_f32_e32 v39, v81, v39
	v_bfe_u32 v44, v40, 16, 1
	v_add3_u32 v40, v40, v44, s10
	v_bfe_u32 v44, v39, 16, 1
	v_lshrrev_b32_e32 v40, 16, v40
	v_add3_u32 v39, v39, v44, s10
	v_and_or_b32 v39, v39, s11, v40
	global_store_dword v[86:87], v39, off
	v_mul_f32_e32 v39, 0x4b800000, v45
	v_cndmask_b32_e32 v39, v45, v39, vcc
	v_rsq_f32_e32 v39, v39
	v_add_u32_e32 v44, s6, v28
	v_ashrrev_i32_e32 v45, 31, v44
	v_lshlrev_b64 v[44:45], 12, v[44:45]
	v_mul_f32_e32 v40, 0x45800000, v39
	v_cndmask_b32_e32 v39, v39, v40, vcc
	v_mul_f32_e32 v40, v41, v39
	v_mul_f32_e32 v40, v80, v40
	v_mul_f32_e32 v39, v85, v39
	v_mul_f32_e32 v39, v81, v39
	v_bfe_u32 v41, v40, 16, 1
	v_add3_u32 v40, v40, v41, s10
	v_bfe_u32 v41, v39, 16, 1
	v_lshrrev_b32_e32 v40, 16, v40
	v_add3_u32 v39, v39, v41, s10
	v_and_or_b32 v39, v39, s11, v40
	v_add_u32_e32 v40, s6, v27
	v_ashrrev_i32_e32 v41, 31, v40
	v_lshlrev_b64 v[40:41], 12, v[40:41]
	v_lshl_add_u64 v[40:41], v[82:83], 0, v[40:41]
	global_store_dword v[40:41], v39, off
	v_mul_f32_e32 v39, 0x4b800000, v46
	v_cndmask_b32_e64 v39, v46, v39, s[4:5]
	v_rsq_f32_e32 v39, v39
	ds_read2_b32 v[40:41], v26 offset0:67 offset1:68
	v_lshl_add_u64 v[44:45], v[82:83], 0, v[44:45]
	v_cmp_gt_f32_e32 vcc, s9, v47
	v_mul_f32_e32 v46, 0x45800000, v39
	v_cndmask_b32_e64 v39, v39, v46, s[4:5]
	v_mul_f32_e32 v42, v42, v39
	v_mul_f32_e32 v42, v80, v42
	s_waitcnt lgkmcnt(0)
	v_mul_f32_e32 v39, v40, v39
	v_mul_f32_e32 v39, v81, v39
	v_bfe_u32 v40, v42, 16, 1
	v_add3_u32 v40, v42, v40, s10
	v_bfe_u32 v42, v39, 16, 1
	v_lshrrev_b32_e32 v40, 16, v40
	v_add3_u32 v39, v39, v42, s10
	v_and_or_b32 v39, v39, s11, v40
	global_store_dword v[44:45], v39, off
	v_mul_f32_e32 v39, 0x4b800000, v47
	v_cndmask_b32_e32 v39, v47, v39, vcc
	v_rsq_f32_e32 v39, v39
	v_add_u32_e32 v44, s6, v30
	v_ashrrev_i32_e32 v45, 31, v44
	v_lshlrev_b64 v[44:45], 12, v[44:45]
	v_mul_f32_e32 v40, 0x45800000, v39
	v_cndmask_b32_e32 v39, v39, v40, vcc
	v_mul_f32_e32 v40, v43, v39
	v_mul_f32_e32 v40, v80, v40
	v_mul_f32_e32 v39, v41, v39
	v_mul_f32_e32 v39, v81, v39
	v_bfe_u32 v41, v40, 16, 1
	v_add3_u32 v40, v40, v41, s10
	v_bfe_u32 v41, v39, 16, 1
	v_lshrrev_b32_e32 v40, 16, v40
	v_add3_u32 v39, v39, v41, s10
	v_and_or_b32 v39, v39, s11, v40
	v_add_u32_e32 v40, s6, v29
	v_ashrrev_i32_e32 v41, 31, v40
	v_lshlrev_b64 v[40:41], 12, v[40:41]
	v_lshl_add_u64 v[40:41], v[82:83], 0, v[40:41]
	global_store_dword v[40:41], v39, off
	ds_read2_b64 v[40:43], v26 offset0:2 offset1:3
	ds_read2_b32 v[76:77], v26 offset0:69 offset1:70
	v_lshl_add_u64 v[78:79], v[82:83], 0, v[44:45]
	ds_read_b128 v[44:47], v1 offset:33552
	ds_read_b128 v[52:55], v1 offset:33808
	ds_read_b128 v[56:59], v1 offset:34064
	ds_read_b128 v[60:63], v1 offset:34320
	ds_read_b128 v[64:67], v1 offset:34576
	ds_read_b128 v[68:71], v1 offset:34832
	s_waitcnt lgkmcnt(5)
	v_pk_add_f32 v[44:45], v[48:49], v[44:45]
	ds_read_b128 v[72:75], v1 offset:35088
	s_waitcnt lgkmcnt(5)
	v_pk_add_f32 v[44:45], v[44:45], v[52:53]
	v_pk_add_f32 v[48:49], v[50:51], 0 op_sel_hi:[1,0]
	s_waitcnt lgkmcnt(4)
	v_pk_add_f32 v[44:45], v[44:45], v[56:57]
	v_pk_add_f32 v[46:47], v[48:49], v[46:47]
	s_waitcnt lgkmcnt(3)
	v_pk_add_f32 v[44:45], v[44:45], v[60:61]
	v_pk_add_f32 v[46:47], v[46:47], v[54:55]
	s_waitcnt lgkmcnt(2)
	v_pk_add_f32 v[44:45], v[44:45], v[64:65]
	v_pk_add_f32 v[46:47], v[46:47], v[58:59]
	s_waitcnt lgkmcnt(1)
	v_pk_add_f32 v[44:45], v[44:45], v[68:69]
	v_pk_add_f32 v[46:47], v[46:47], v[62:63]
	s_waitcnt lgkmcnt(0)
	v_pk_add_f32 v[44:45], v[44:45], v[72:73]
	v_pk_add_f32 v[46:47], v[46:47], v[66:67]
	v_pk_fma_f32 v[44:45], v[44:45], s[2:3], v[6:7] op_sel_hi:[1,0,0]
	v_pk_add_f32 v[46:47], v[46:47], v[70:71]
	v_mul_f32_e32 v39, 0x4b800000, v44
	v_cmp_gt_f32_e64 s[4:5], s9, v44
	v_cmp_gt_f32_e32 vcc, s9, v45
	v_pk_add_f32 v[46:47], v[46:47], v[74:75]
	v_cndmask_b32_e64 v39, v44, v39, s[4:5]
	v_rsq_f32_e32 v39, v39
	v_pk_fma_f32 v[46:47], v[46:47], s[2:3], v[6:7] op_sel_hi:[1,0,0]
	s_add_i32 s3, s3, s8
	s_cmpk_gt_i32 s13, 0x3ff
	v_mul_f32_e32 v44, 0x45800000, v39
	v_cndmask_b32_e64 v39, v39, v44, s[4:5]
	v_mul_f32_e32 v40, v40, v39
	v_mul_f32_e32 v40, v80, v40
	v_mul_f32_e32 v39, v76, v39
	v_mul_f32_e32 v39, v81, v39
	v_bfe_u32 v44, v40, 16, 1
	v_add3_u32 v40, v40, v44, s10
	v_bfe_u32 v44, v39, 16, 1
	v_lshrrev_b32_e32 v40, 16, v40
	v_add3_u32 v39, v39, v44, s10
	v_and_or_b32 v39, v39, s11, v40
	global_store_dword v[78:79], v39, off
	v_mul_f32_e32 v39, 0x4b800000, v45
	v_cndmask_b32_e32 v39, v45, v39, vcc
	v_rsq_f32_e32 v39, v39
	v_cmp_gt_f32_e64 s[4:5], s9, v46
	v_add_u32_e32 v44, s6, v32
	v_ashrrev_i32_e32 v45, 31, v44
	v_mul_f32_e32 v40, 0x45800000, v39
	v_cndmask_b32_e32 v39, v39, v40, vcc
	v_mul_f32_e32 v40, v41, v39
	v_mul_f32_e32 v40, v80, v40
	v_mul_f32_e32 v39, v77, v39
	v_mul_f32_e32 v39, v81, v39
	v_bfe_u32 v41, v40, 16, 1
	v_add3_u32 v40, v40, v41, s10
	v_bfe_u32 v41, v39, 16, 1
	v_lshrrev_b32_e32 v40, 16, v40
	v_add3_u32 v39, v39, v41, s10
	v_and_or_b32 v39, v39, s11, v40
	v_add_u32_e32 v40, s6, v31
	v_ashrrev_i32_e32 v41, 31, v40
	v_lshlrev_b64 v[40:41], 12, v[40:41]
	v_lshl_add_u64 v[40:41], v[82:83], 0, v[40:41]
	global_store_dword v[40:41], v39, off
	v_mul_f32_e32 v39, 0x4b800000, v46
	v_cndmask_b32_e64 v39, v46, v39, s[4:5]
	v_rsq_f32_e32 v39, v39
	ds_read2_b32 v[40:41], v26 offset0:71 offset1:72
	v_lshlrev_b64 v[44:45], 12, v[44:45]
	v_lshl_add_u64 v[44:45], v[82:83], 0, v[44:45]
	v_mul_f32_e32 v46, 0x45800000, v39
	v_cndmask_b32_e64 v39, v39, v46, s[4:5]
	v_mul_f32_e32 v42, v42, v39
	v_mul_f32_e32 v42, v80, v42
	s_waitcnt lgkmcnt(0)
	v_mul_f32_e32 v39, v40, v39
	v_mul_f32_e32 v39, v81, v39
	v_bfe_u32 v40, v42, 16, 1
	v_add3_u32 v40, v42, v40, s10
	v_bfe_u32 v42, v39, 16, 1
	v_lshrrev_b32_e32 v40, 16, v40
	v_add3_u32 v39, v39, v42, s10
	v_and_or_b32 v39, v39, s11, v40
	v_cmp_gt_f32_e32 vcc, s9, v47
	global_store_dword v[44:45], v39, off
	v_mul_f32_e32 v39, 0x4b800000, v47
	v_cndmask_b32_e32 v39, v47, v39, vcc
	v_rsq_f32_e32 v39, v39
	s_nop 0
	v_mul_f32_e32 v40, 0x45800000, v39
	v_cndmask_b32_e32 v39, v39, v40, vcc
	v_mul_f32_e32 v40, v43, v39
	v_mul_f32_e32 v40, v80, v40
	v_mul_f32_e32 v39, v41, v39
	v_mul_f32_e32 v39, v81, v39
	v_bfe_u32 v41, v40, 16, 1
	v_add3_u32 v40, v40, v41, s10
	v_bfe_u32 v41, v39, 16, 1
	v_lshrrev_b32_e32 v40, 16, v40
	v_add3_u32 v39, v39, v41, s10
	v_and_or_b32 v39, v39, s11, v40
	v_add_u32_e32 v40, s6, v33
	v_ashrrev_i32_e32 v41, 31, v40
	v_lshlrev_b64 v[40:41], 12, v[40:41]
	v_lshl_add_u64 v[40:41], v[82:83], 0, v[40:41]
	global_store_dword v[40:41], v39, off
	s_barrier
	s_cbranch_scc0 .LBB0_783
